# barriers: non-leaders invalidate L1 before polling, leader releases its XCD before its own invalidate
# speedup vs baseline: 1.0210x; 1.0210x over previous
; __device__ __forceinline__ unsigned xb_ld(unsigned* p)              { return __hip_atomic_load(p, __ATOMIC_RELAXED, __HIP_MEMORY_SCOPE_AGENT); }
; __device__ __forceinline__ unsigned xb_add(unsigned* p, unsigned v) { return __hip_atomic_fetch_add(p, v, __ATOMIC_RELAXED, __HIP_MEMORY_SCOPE_AGENT); }
; #define XB_SPIN(cond, bar) do { unsigned _sp = 0; while (cond) { __builtin_amdgcn_s_sleep(1); \
;     if ((++_sp & 255u) == 0u) { if (xb_ld(&(bar)[XB_TMO])) break; if (_sp > XB_SPIN_CAP) { atomicAdd(&(bar)[XB_TMO], 1u); break; } } } } while (0)
; __device__ __forceinline__ void xcd_barrier(const XcdBarrier& b, bool tid0) {
;     ...
;         const unsigned old = xb_add(&bar[XB_XSUB(b.x)], 1u);
;         const unsigned gen = old / nloc;
;         if (old + 1u == (gen + 1u) * nloc) {
;             __builtin_amdgcn_fence(__ATOMIC_RELEASE, "agent");
;             asm volatile("s_waitcnt vmcnt(0)" ::: "memory");
;             const unsigned og = xb_add(&bar[XB_TOP], 1u);
;             const unsigned tg = og / nx;
;             if (og + 1u == (tg + 1u) * nx) xb_add(&bar[XB_TOPGEN], 1u);
;             else XB_SPIN(xb_ld(&bar[XB_TOPGEN]) == tg, bar);
;             __builtin_amdgcn_fence(__ATOMIC_ACQUIRE, "agent");
;             xb_add(&bar[XB_XGEN(b.x)], 1u);
;             asm volatile("s_waitcnt vmcnt(0)" ::: "memory");
;         } else {
;             XB_SPIN(xb_ld(&bar[XB_XGEN(b.x)]) == gen, bar);
;             __builtin_amdgcn_fence(__ATOMIC_ACQUIRE, "agent");
;             asm volatile("s_waitcnt vmcnt(0)" ::: "memory");
.LBB0_189:
	s_or_b64 exec, exec, s[8:9]
	v_cvt_f32_u32_e32 v4, v2
	s_waitcnt vmcnt(0)
	v_readfirstlane_b32 s0, v3
	v_sub_u32_e32 v3, 0, v2
	v_rcp_iflag_f32_e32 v4, v4
	v_add_u32_e32 v5, s0, v1
	v_mul_f32_e32 v4, 0x4f7ffffe, v4
	v_cvt_u32_f32_e32 v4, v4
	v_mul_lo_u32 v1, v3, v4
	v_mul_hi_u32 v1, v4, v1
	v_add_u32_e32 v1, v4, v1
	v_mul_hi_u32 v1, v5, v1
	v_mul_lo_u32 v3, v1, v2
	v_sub_u32_e32 v3, v5, v3
	v_add_u32_e32 v4, 1, v1
	v_cmp_ge_u32_e32 vcc, v3, v2
	s_nop 1
	v_cndmask_b32_e32 v1, v1, v4, vcc
	v_sub_u32_e32 v4, v3, v2
	v_cndmask_b32_e32 v3, v3, v4, vcc
	v_add_u32_e32 v4, 1, v1
	v_cmp_ge_u32_e32 vcc, v3, v2
	v_add_u32_e32 v3, 1, v5
	s_nop 0
	v_cndmask_b32_e32 v1, v1, v4, vcc
	v_mul_lo_u32 v4, v2, v1
	v_add_u32_e32 v2, v4, v2
	v_cmp_ne_u32_e32 vcc, v3, v2
	s_and_saveexec_b64 s[0:1], vcc
	s_xor_b64 s[8:9], exec, s[0:1]
	s_cbranch_execz .LBB0_203
	s_waitcnt lgkmcnt(0)
	buffer_inv sc1
	global_load_dword v0, v254, s[6:7] offset:1024 sc1
	s_add_u32 s14, s6, 0x2400
	s_addc_u32 s15, s7, 0
	s_waitcnt vmcnt(0)
	v_cmp_eq_u32_e32 vcc, v0, v1
	s_and_saveexec_b64 s[10:11], vcc
	s_cbranch_execz .LBB0_202
	s_add_u32 s12, s4, 0x26120200
	s_addc_u32 s13, s5, 0
	s_mov_b32 s21, 1
	s_mov_b64 s[24:25], 0
	s_branch .LBB0_193

; __device__ __forceinline__ unsigned xb_ld(unsigned* p)              { return __hip_atomic_load(p, __ATOMIC_RELAXED, __HIP_MEMORY_SCOPE_AGENT); }
; #define XB_SPIN(cond, bar) do { unsigned _sp = 0; while (cond) { __builtin_amdgcn_s_sleep(1); \
;     if ((++_sp & 255u) == 0u) { if (xb_ld(&(bar)[XB_TMO])) break; if (_sp > XB_SPIN_CAP) { atomicAdd(&(bar)[XB_TMO], 1u); break; } } } } while (0)
; __device__ __forceinline__ void xcd_barrier(const XcdBarrier& b, bool tid0) {
;     ...
;             XB_SPIN(xb_ld(&bar[XB_XGEN(b.x)]) == gen, bar);
;             __builtin_amdgcn_fence(__ATOMIC_ACQUIRE, "agent");
;             asm volatile("s_waitcnt vmcnt(0)" ::: "memory");
.LBB0_202:
	s_or_b64 exec, exec, s[10:11]
	s_waitcnt vmcnt(0)
	s_waitcnt vmcnt(0)

; __device__ __forceinline__ unsigned xb_ld(unsigned* p)              { return __hip_atomic_load(p, __ATOMIC_RELAXED, __HIP_MEMORY_SCOPE_AGENT); }
; __device__ __forceinline__ unsigned xb_add(unsigned* p, unsigned v) { return __hip_atomic_fetch_add(p, v, __ATOMIC_RELAXED, __HIP_MEMORY_SCOPE_AGENT); }
; #define XB_SPIN(cond, bar) do { unsigned _sp = 0; while (cond) { __builtin_amdgcn_s_sleep(1); \
;     if ((++_sp & 255u) == 0u) { if (xb_ld(&(bar)[XB_TMO])) break; if (_sp > XB_SPIN_CAP) { atomicAdd(&(bar)[XB_TMO], 1u); break; } } } } while (0)
; __device__ __forceinline__ void xcd_barrier(const XcdBarrier& b, bool tid0) {
;     ...
;             const unsigned og = xb_add(&bar[XB_TOP], 1u);
;             const unsigned tg = og / nx;
;             if (og + 1u == (tg + 1u) * nx) xb_add(&bar[XB_TOPGEN], 1u);
;             else XB_SPIN(xb_ld(&bar[XB_TOPGEN]) == tg, bar);
;             __builtin_amdgcn_fence(__ATOMIC_ACQUIRE, "agent");
;             xb_add(&bar[XB_XGEN(b.x)], 1u);
;             asm volatile("s_waitcnt vmcnt(0)" ::: "memory");
.LBB0_220:
	s_or_b64 exec, exec, s[4:5]
	s_mov_b64 s[0:1], exec
	v_mbcnt_lo_u32_b32 v0, s0, 0
	v_mbcnt_hi_u32_b32 v0, s1, v0
	v_cmp_eq_u32_e32 vcc, 0, v0
	s_waitcnt vmcnt(0)
	s_and_saveexec_b64 s[4:5], vcc
	s_cbranch_execz .LBB0_222
	s_bcnt1_i32_b64 s0, s[0:1]
	v_mov_b32_e32 v0, s0
	global_atomic_add v254, v0, s[6:7] offset:1024
.LBB0_222:
	s_or_b64 exec, exec, s[4:5]
	buffer_inv sc1
	s_waitcnt vmcnt(0)

; __device__ __forceinline__ unsigned xb_ld(unsigned* p)              { return __hip_atomic_load(p, __ATOMIC_RELAXED, __HIP_MEMORY_SCOPE_AGENT); }
; __device__ __forceinline__ unsigned xb_add(unsigned* p, unsigned v) { return __hip_atomic_fetch_add(p, v, __ATOMIC_RELAXED, __HIP_MEMORY_SCOPE_AGENT); }
; #define XB_SPIN(cond, bar) do { unsigned _sp = 0; while (cond) { __builtin_amdgcn_s_sleep(1); \
;     if ((++_sp & 255u) == 0u) { if (xb_ld(&(bar)[XB_TMO])) break; if (_sp > XB_SPIN_CAP) { atomicAdd(&(bar)[XB_TMO], 1u); break; } } } } while (0)
; __device__ __forceinline__ void xcd_barrier(const XcdBarrier& b, bool tid0) {
;     ...
;         const unsigned old = xb_add(&bar[XB_XSUB(b.x)], 1u);
;         const unsigned gen = old / nloc;
;         if (old + 1u == (gen + 1u) * nloc) {
;             __builtin_amdgcn_fence(__ATOMIC_RELEASE, "agent");
;             asm volatile("s_waitcnt vmcnt(0)" ::: "memory");
;             const unsigned og = xb_add(&bar[XB_TOP], 1u);
;             const unsigned tg = og / nx;
;             if (og + 1u == (tg + 1u) * nx) xb_add(&bar[XB_TOPGEN], 1u);
;             else XB_SPIN(xb_ld(&bar[XB_TOPGEN]) == tg, bar);
;             __builtin_amdgcn_fence(__ATOMIC_ACQUIRE, "agent");
;             xb_add(&bar[XB_XGEN(b.x)], 1u);
;             asm volatile("s_waitcnt vmcnt(0)" ::: "memory");
;         } else {
;             XB_SPIN(xb_ld(&bar[XB_XGEN(b.x)]) == gen, bar);
;             __builtin_amdgcn_fence(__ATOMIC_ACQUIRE, "agent");
;             asm volatile("s_waitcnt vmcnt(0)" ::: "memory");
.LBB0_261:
	s_or_b64 exec, exec, s[8:9]
	v_cvt_f32_u32_e32 v4, v2
	s_waitcnt vmcnt(0)
	v_readfirstlane_b32 s0, v3
	v_sub_u32_e32 v3, 0, v2
	v_rcp_iflag_f32_e32 v4, v4
	v_add_u32_e32 v5, s0, v1
	v_mul_f32_e32 v4, 0x4f7ffffe, v4
	v_cvt_u32_f32_e32 v4, v4
	v_mul_lo_u32 v1, v3, v4
	v_mul_hi_u32 v1, v4, v1
	v_add_u32_e32 v1, v4, v1
	v_mul_hi_u32 v1, v5, v1
	v_mul_lo_u32 v3, v1, v2
	v_sub_u32_e32 v3, v5, v3
	v_add_u32_e32 v4, 1, v1
	v_cmp_ge_u32_e32 vcc, v3, v2
	s_nop 1
	v_cndmask_b32_e32 v1, v1, v4, vcc
	v_sub_u32_e32 v4, v3, v2
	v_cndmask_b32_e32 v3, v3, v4, vcc
	v_add_u32_e32 v4, 1, v1
	v_cmp_ge_u32_e32 vcc, v3, v2
	v_add_u32_e32 v3, 1, v5
	s_nop 0
	v_cndmask_b32_e32 v1, v1, v4, vcc
	v_mul_lo_u32 v4, v2, v1
	v_add_u32_e32 v2, v4, v2
	v_cmp_ne_u32_e32 vcc, v3, v2
	s_and_saveexec_b64 s[0:1], vcc
	s_xor_b64 s[8:9], exec, s[0:1]
	s_cbranch_execz .LBB0_275
	s_waitcnt lgkmcnt(0)
	buffer_inv sc1
	global_load_dword v0, v254, s[6:7] offset:1024 sc1
	s_add_u32 s12, s6, 0x2400
	s_addc_u32 s13, s7, 0
	s_waitcnt vmcnt(0)
	v_cmp_eq_u32_e32 vcc, v0, v1
	s_and_saveexec_b64 s[10:11], vcc
	s_cbranch_execz .LBB0_274
	s_mov_b32 s19, 1
	s_mov_b64 s[14:15], 0
	s_branch .LBB0_265

; __device__ __forceinline__ unsigned xb_add(unsigned* p, unsigned v) { return __hip_atomic_fetch_add(p, v, __ATOMIC_RELAXED, __HIP_MEMORY_SCOPE_AGENT); }
; __device__ __forceinline__ void xcd_barrier(const XcdBarrier& b, bool tid0) {
;     ...
;             __builtin_amdgcn_fence(__ATOMIC_ACQUIRE, "agent");
;             xb_add(&bar[XB_XGEN(b.x)], 1u);
.Lfastbar_0:
	s_mov_b64 s[0:1], exec
	v_mbcnt_lo_u32_b32 v0, s0, 0
	v_mbcnt_hi_u32_b32 v0, s1, v0
	v_cmp_eq_u32_e32 vcc, 0, v0
	s_waitcnt vmcnt(0)
	s_and_saveexec_b64 s[4:5], vcc
	s_cbranch_execz .LBB0_294
	s_bcnt1_i32_b64 s0, s[0:1]
	v_mov_b32_e32 v0, s0
	global_atomic_add v254, v0, s[6:7] offset:1024

; __device__ __forceinline__ unsigned xb_ld(unsigned* p)              { return __hip_atomic_load(p, __ATOMIC_RELAXED, __HIP_MEMORY_SCOPE_AGENT); }
; __device__ __forceinline__ unsigned xb_add(unsigned* p, unsigned v) { return __hip_atomic_fetch_add(p, v, __ATOMIC_RELAXED, __HIP_MEMORY_SCOPE_AGENT); }
; #define XB_SPIN(cond, bar) do { unsigned _sp = 0; while (cond) { __builtin_amdgcn_s_sleep(1); \
;     if ((++_sp & 255u) == 0u) { if (xb_ld(&(bar)[XB_TMO])) break; if (_sp > XB_SPIN_CAP) { atomicAdd(&(bar)[XB_TMO], 1u); break; } } } } while (0)
; __device__ __forceinline__ void xcd_barrier(const XcdBarrier& b, bool tid0) {
;     ...
;         const unsigned old = xb_add(&bar[XB_XSUB(b.x)], 1u);
;         const unsigned gen = old / nloc;
;         if (old + 1u == (gen + 1u) * nloc) {
;             __builtin_amdgcn_fence(__ATOMIC_RELEASE, "agent");
;             asm volatile("s_waitcnt vmcnt(0)" ::: "memory");
;             const unsigned og = xb_add(&bar[XB_TOP], 1u);
;             const unsigned tg = og / nx;
;             if (og + 1u == (tg + 1u) * nx) xb_add(&bar[XB_TOPGEN], 1u);
;             else XB_SPIN(xb_ld(&bar[XB_TOPGEN]) == tg, bar);
;             __builtin_amdgcn_fence(__ATOMIC_ACQUIRE, "agent");
;             xb_add(&bar[XB_XGEN(b.x)], 1u);
;             asm volatile("s_waitcnt vmcnt(0)" ::: "memory");
;         } else {
;             XB_SPIN(xb_ld(&bar[XB_XGEN(b.x)]) == gen, bar);
;             __builtin_amdgcn_fence(__ATOMIC_ACQUIRE, "agent");
;             asm volatile("s_waitcnt vmcnt(0)" ::: "memory");
.LBB0_384:
	s_or_b64 exec, exec, s[8:9]
	v_cvt_f32_u32_e32 v4, v2
	s_waitcnt vmcnt(0)
	v_readfirstlane_b32 s0, v3
	v_sub_u32_e32 v3, 0, v2
	v_rcp_iflag_f32_e32 v4, v4
	v_add_u32_e32 v5, s0, v1
	v_mul_f32_e32 v4, 0x4f7ffffe, v4
	v_cvt_u32_f32_e32 v4, v4
	v_mul_lo_u32 v1, v3, v4
	v_mul_hi_u32 v1, v4, v1
	v_add_u32_e32 v1, v4, v1
	v_mul_hi_u32 v1, v5, v1
	v_mul_lo_u32 v3, v1, v2
	v_sub_u32_e32 v3, v5, v3
	v_add_u32_e32 v4, 1, v1
	v_cmp_ge_u32_e32 vcc, v3, v2
	s_nop 1
	v_cndmask_b32_e32 v1, v1, v4, vcc
	v_sub_u32_e32 v4, v3, v2
	v_cndmask_b32_e32 v3, v3, v4, vcc
	v_add_u32_e32 v4, 1, v1
	v_cmp_ge_u32_e32 vcc, v3, v2
	v_add_u32_e32 v3, 1, v5
	s_nop 0
	v_cndmask_b32_e32 v1, v1, v4, vcc
	v_mul_lo_u32 v4, v2, v1
	v_add_u32_e32 v2, v4, v2
	v_cmp_ne_u32_e32 vcc, v3, v2
	s_and_saveexec_b64 s[0:1], vcc
	s_xor_b64 s[8:9], exec, s[0:1]
	s_cbranch_execz .LBB0_398
	s_waitcnt lgkmcnt(0)
	buffer_inv sc1
	global_load_dword v0, v254, s[6:7] offset:1024 sc1
	s_add_u32 s14, s6, 0x2400
	s_addc_u32 s15, s7, 0
	s_waitcnt vmcnt(0)
	v_cmp_eq_u32_e32 vcc, v0, v1
	s_and_saveexec_b64 s[10:11], vcc
	s_cbranch_execz .LBB0_397
	s_add_u32 s12, s4, 0x26120200
	s_addc_u32 s13, s5, 0
	s_mov_b32 s21, 1
	s_mov_b64 s[26:27], 0
	s_branch .LBB0_388

; __device__ __forceinline__ unsigned xb_ld(unsigned* p)              { return __hip_atomic_load(p, __ATOMIC_RELAXED, __HIP_MEMORY_SCOPE_AGENT); }
; __device__ __forceinline__ unsigned xb_add(unsigned* p, unsigned v) { return __hip_atomic_fetch_add(p, v, __ATOMIC_RELAXED, __HIP_MEMORY_SCOPE_AGENT); }
; #define XB_SPIN(cond, bar) do { unsigned _sp = 0; while (cond) { __builtin_amdgcn_s_sleep(1); \
;     if ((++_sp & 255u) == 0u) { if (xb_ld(&(bar)[XB_TMO])) break; if (_sp > XB_SPIN_CAP) { atomicAdd(&(bar)[XB_TMO], 1u); break; } } } } while (0)
; __device__ __forceinline__ void xcd_barrier(const XcdBarrier& b, bool tid0) {
;     ...
;         const unsigned old = xb_add(&bar[XB_XSUB(b.x)], 1u);
;         const unsigned gen = old / nloc;
;         if (old + 1u == (gen + 1u) * nloc) {
;             __builtin_amdgcn_fence(__ATOMIC_RELEASE, "agent");
;             asm volatile("s_waitcnt vmcnt(0)" ::: "memory");
;             const unsigned og = xb_add(&bar[XB_TOP], 1u);
;             const unsigned tg = og / nx;
;             if (og + 1u == (tg + 1u) * nx) xb_add(&bar[XB_TOPGEN], 1u);
;             else XB_SPIN(xb_ld(&bar[XB_TOPGEN]) == tg, bar);
;             __builtin_amdgcn_fence(__ATOMIC_ACQUIRE, "agent");
;             xb_add(&bar[XB_XGEN(b.x)], 1u);
;             asm volatile("s_waitcnt vmcnt(0)" ::: "memory");
;         } else {
;             XB_SPIN(xb_ld(&bar[XB_XGEN(b.x)]) == gen, bar);
;             __builtin_amdgcn_fence(__ATOMIC_ACQUIRE, "agent");
;             asm volatile("s_waitcnt vmcnt(0)" ::: "memory");
.LBB0_557:
	s_or_b64 exec, exec, s[8:9]
	v_cvt_f32_u32_e32 v4, v2
	s_waitcnt vmcnt(0)
	v_readfirstlane_b32 s0, v3
	v_sub_u32_e32 v3, 0, v2
	v_rcp_iflag_f32_e32 v4, v4
	v_add_u32_e32 v5, s0, v1
	v_mul_f32_e32 v4, 0x4f7ffffe, v4
	v_cvt_u32_f32_e32 v4, v4
	v_mul_lo_u32 v1, v3, v4
	v_mul_hi_u32 v1, v4, v1
	v_add_u32_e32 v1, v4, v1
	v_mul_hi_u32 v1, v5, v1
	v_mul_lo_u32 v3, v1, v2
	v_sub_u32_e32 v3, v5, v3
	v_add_u32_e32 v4, 1, v1
	v_cmp_ge_u32_e32 vcc, v3, v2
	s_nop 1
	v_cndmask_b32_e32 v1, v1, v4, vcc
	v_sub_u32_e32 v4, v3, v2
	v_cndmask_b32_e32 v3, v3, v4, vcc
	v_add_u32_e32 v4, 1, v1
	v_cmp_ge_u32_e32 vcc, v3, v2
	v_add_u32_e32 v3, 1, v5
	s_nop 0
	v_cndmask_b32_e32 v1, v1, v4, vcc
	v_mul_lo_u32 v4, v2, v1
	v_add_u32_e32 v2, v4, v2
	v_cmp_ne_u32_e32 vcc, v3, v2
	s_and_saveexec_b64 s[0:1], vcc
	s_xor_b64 s[8:9], exec, s[0:1]
	s_cbranch_execz .LBB0_571
	s_waitcnt lgkmcnt(0)
	buffer_inv sc1
	global_load_dword v0, v254, s[6:7] offset:1024 sc1
	s_add_u32 s12, s6, 0x2400
	s_addc_u32 s13, s7, 0
	s_waitcnt vmcnt(0)
	v_cmp_eq_u32_e32 vcc, v0, v1
	s_and_saveexec_b64 s[10:11], vcc
	s_cbranch_execz .LBB0_570
	s_mov_b32 s21, 1
	s_mov_b64 s[14:15], 0
	s_branch .LBB0_561

; __device__ __forceinline__ unsigned xb_ld(unsigned* p)              { return __hip_atomic_load(p, __ATOMIC_RELAXED, __HIP_MEMORY_SCOPE_AGENT); }
; __device__ __forceinline__ unsigned xb_add(unsigned* p, unsigned v) { return __hip_atomic_fetch_add(p, v, __ATOMIC_RELAXED, __HIP_MEMORY_SCOPE_AGENT); }
; #define XB_SPIN(cond, bar) do { unsigned _sp = 0; while (cond) { __builtin_amdgcn_s_sleep(1); \
;     if ((++_sp & 255u) == 0u) { if (xb_ld(&(bar)[XB_TMO])) break; if (_sp > XB_SPIN_CAP) { atomicAdd(&(bar)[XB_TMO], 1u); break; } } } } while (0)
; __device__ __forceinline__ void xcd_barrier(const XcdBarrier& b, bool tid0) {
;     ...
;         const unsigned old = xb_add(&bar[XB_XSUB(b.x)], 1u);
;         const unsigned gen = old / nloc;
;         if (old + 1u == (gen + 1u) * nloc) {
;             __builtin_amdgcn_fence(__ATOMIC_RELEASE, "agent");
;             asm volatile("s_waitcnt vmcnt(0)" ::: "memory");
;             const unsigned og = xb_add(&bar[XB_TOP], 1u);
;             const unsigned tg = og / nx;
;             if (og + 1u == (tg + 1u) * nx) xb_add(&bar[XB_TOPGEN], 1u);
;             else XB_SPIN(xb_ld(&bar[XB_TOPGEN]) == tg, bar);
;             __builtin_amdgcn_fence(__ATOMIC_ACQUIRE, "agent");
;             xb_add(&bar[XB_XGEN(b.x)], 1u);
;             asm volatile("s_waitcnt vmcnt(0)" ::: "memory");
;         } else {
;             XB_SPIN(xb_ld(&bar[XB_XGEN(b.x)]) == gen, bar);
;             __builtin_amdgcn_fence(__ATOMIC_ACQUIRE, "agent");
;             asm volatile("s_waitcnt vmcnt(0)" ::: "memory");
.LBB0_731:
	s_or_b64 exec, exec, s[12:13]
	v_cvt_f32_u32_e32 v4, v2
	s_waitcnt vmcnt(0)
	v_readfirstlane_b32 s0, v3
	v_sub_u32_e32 v3, 0, v2
	v_rcp_iflag_f32_e32 v4, v4
	v_add_u32_e32 v5, s0, v1
	v_mul_f32_e32 v4, 0x4f7ffffe, v4
	v_cvt_u32_f32_e32 v4, v4
	v_mul_lo_u32 v1, v3, v4
	v_mul_hi_u32 v1, v4, v1
	v_add_u32_e32 v1, v4, v1
	v_mul_hi_u32 v1, v5, v1
	v_mul_lo_u32 v3, v1, v2
	v_sub_u32_e32 v3, v5, v3
	v_add_u32_e32 v4, 1, v1
	v_cmp_ge_u32_e32 vcc, v3, v2
	s_nop 1
	v_cndmask_b32_e32 v1, v1, v4, vcc
	v_sub_u32_e32 v4, v3, v2
	v_cndmask_b32_e32 v3, v3, v4, vcc
	v_add_u32_e32 v4, 1, v1
	v_cmp_ge_u32_e32 vcc, v3, v2
	v_add_u32_e32 v3, 1, v5
	s_nop 0
	v_cndmask_b32_e32 v1, v1, v4, vcc
	v_mul_lo_u32 v4, v2, v1
	v_add_u32_e32 v2, v4, v2
	v_cmp_ne_u32_e32 vcc, v3, v2
	s_and_saveexec_b64 s[0:1], vcc
	s_xor_b64 s[12:13], exec, s[0:1]
	s_cbranch_execz .LBB0_745
	s_waitcnt lgkmcnt(0)
	buffer_inv sc1
	global_load_dword v0, v254, s[10:11] offset:1024 sc1
	s_add_u32 s24, s10, 0x2400
	s_addc_u32 s25, s11, 0
	s_waitcnt vmcnt(0)
	v_cmp_eq_u32_e32 vcc, v0, v1
	s_and_saveexec_b64 s[14:15], vcc
	s_cbranch_execz .LBB0_744
	s_mov_b32 s36, 1
	s_mov_b64 s[26:27], 0
	s_branch .LBB0_735

; __device__ __forceinline__ unsigned xb_ld(unsigned* p)              { return __hip_atomic_load(p, __ATOMIC_RELAXED, __HIP_MEMORY_SCOPE_AGENT); }
; #define XB_SPIN(cond, bar) do { unsigned _sp = 0; while (cond) { __builtin_amdgcn_s_sleep(1); \
;     if ((++_sp & 255u) == 0u) { if (xb_ld(&(bar)[XB_TMO])) break; if (_sp > XB_SPIN_CAP) { atomicAdd(&(bar)[XB_TMO], 1u); break; } } } } while (0)
; __device__ __forceinline__ void xcd_barrier(const XcdBarrier& b, bool tid0) {
;     ...
;             XB_SPIN(xb_ld(&bar[XB_XGEN(b.x)]) == gen, bar);
;             __builtin_amdgcn_fence(__ATOMIC_ACQUIRE, "agent");
;             asm volatile("s_waitcnt vmcnt(0)" ::: "memory");
.LBB0_744:
	s_or_b64 exec, exec, s[14:15]
	s_waitcnt vmcnt(0)
	s_waitcnt vmcnt(0)

; __device__ __forceinline__ unsigned xb_add(unsigned* p, unsigned v) { return __hip_atomic_fetch_add(p, v, __ATOMIC_RELAXED, __HIP_MEMORY_SCOPE_AGENT); }
; __device__ __forceinline__ void xcd_barrier(const XcdBarrier& b, bool tid0) {
;     ...
;             __builtin_amdgcn_fence(__ATOMIC_ACQUIRE, "agent");
;             xb_add(&bar[XB_XGEN(b.x)], 1u);
.Lfastbar_6:
	s_mov_b64 s[0:1], exec
	v_mbcnt_lo_u32_b32 v0, s0, 0
	v_mbcnt_hi_u32_b32 v0, s1, v0
	v_cmp_eq_u32_e32 vcc, 0, v0
	s_waitcnt vmcnt(0)
	s_and_saveexec_b64 s[8:9], vcc
	s_cbranch_execz .LBB0_764
	s_bcnt1_i32_b64 s0, s[0:1]
	v_mov_b32_e32 v0, s0
	global_atomic_add v254, v0, s[10:11] offset:1024
.LBB0_764:
	s_or_b64 exec, exec, s[8:9]
	buffer_inv sc1
	s_waitcnt vmcnt(0)

; __device__ __forceinline__ unsigned xb_ld(unsigned* p)              { return __hip_atomic_load(p, __ATOMIC_RELAXED, __HIP_MEMORY_SCOPE_AGENT); }
; __device__ __forceinline__ unsigned xb_add(unsigned* p, unsigned v) { return __hip_atomic_fetch_add(p, v, __ATOMIC_RELAXED, __HIP_MEMORY_SCOPE_AGENT); }
; #define XB_SPIN(cond, bar) do { unsigned _sp = 0; while (cond) { __builtin_amdgcn_s_sleep(1); \
;     if ((++_sp & 255u) == 0u) { if (xb_ld(&(bar)[XB_TMO])) break; if (_sp > XB_SPIN_CAP) { atomicAdd(&(bar)[XB_TMO], 1u); break; } } } } while (0)
; __device__ __forceinline__ void xcd_barrier(const XcdBarrier& b, bool tid0) {
;     ...
;         const unsigned old = xb_add(&bar[XB_XSUB(b.x)], 1u);
;         const unsigned gen = old / nloc;
;         if (old + 1u == (gen + 1u) * nloc) {
;             __builtin_amdgcn_fence(__ATOMIC_RELEASE, "agent");
;             asm volatile("s_waitcnt vmcnt(0)" ::: "memory");
;             const unsigned og = xb_add(&bar[XB_TOP], 1u);
;             const unsigned tg = og / nx;
;             if (og + 1u == (tg + 1u) * nx) xb_add(&bar[XB_TOPGEN], 1u);
;             else XB_SPIN(xb_ld(&bar[XB_TOPGEN]) == tg, bar);
;             __builtin_amdgcn_fence(__ATOMIC_ACQUIRE, "agent");
;             xb_add(&bar[XB_XGEN(b.x)], 1u);
;             asm volatile("s_waitcnt vmcnt(0)" ::: "memory");
;         } else {
;             XB_SPIN(xb_ld(&bar[XB_XGEN(b.x)]) == gen, bar);
;             __builtin_amdgcn_fence(__ATOMIC_ACQUIRE, "agent");
;             asm volatile("s_waitcnt vmcnt(0)" ::: "memory");
.LBB0_825:
	s_or_b64 exec, exec, s[10:11]
	v_cvt_f32_u32_e32 v4, v2
	s_waitcnt vmcnt(0)
	v_readfirstlane_b32 s0, v3
	v_sub_u32_e32 v3, 0, v2
	v_rcp_iflag_f32_e32 v4, v4
	v_add_u32_e32 v5, s0, v1
	v_mul_f32_e32 v4, 0x4f7ffffe, v4
	v_cvt_u32_f32_e32 v4, v4
	v_mul_lo_u32 v1, v3, v4
	v_mul_hi_u32 v1, v4, v1
	v_add_u32_e32 v1, v4, v1
	v_mul_hi_u32 v1, v5, v1
	v_mul_lo_u32 v3, v1, v2
	v_sub_u32_e32 v3, v5, v3
	v_add_u32_e32 v4, 1, v1
	v_cmp_ge_u32_e32 vcc, v3, v2
	s_nop 1
	v_cndmask_b32_e32 v1, v1, v4, vcc
	v_sub_u32_e32 v4, v3, v2
	v_cndmask_b32_e32 v3, v3, v4, vcc
	v_add_u32_e32 v4, 1, v1
	v_cmp_ge_u32_e32 vcc, v3, v2
	v_add_u32_e32 v3, 1, v5
	s_nop 0
	v_cndmask_b32_e32 v1, v1, v4, vcc
	v_mul_lo_u32 v4, v2, v1
	v_add_u32_e32 v2, v4, v2
	v_cmp_ne_u32_e32 vcc, v3, v2
	s_and_saveexec_b64 s[0:1], vcc
	s_xor_b64 s[10:11], exec, s[0:1]
	s_cbranch_execz .LBB0_839
	s_waitcnt lgkmcnt(0)
	buffer_inv sc1
	global_load_dword v0, v254, s[8:9] offset:1024 sc1
	s_add_u32 s14, s8, 0x2400
	s_addc_u32 s15, s9, 0
	s_waitcnt vmcnt(0)
	v_cmp_eq_u32_e32 vcc, v0, v1
	s_and_saveexec_b64 s[12:13], vcc
	s_cbranch_execz .LBB0_838
	s_mov_b32 s34, 1
	s_mov_b64 s[24:25], 0
	s_branch .LBB0_829

; __device__ __forceinline__ unsigned xb_ld(unsigned* p)              { return __hip_atomic_load(p, __ATOMIC_RELAXED, __HIP_MEMORY_SCOPE_AGENT); }
; #define XB_SPIN(cond, bar) do { unsigned _sp = 0; while (cond) { __builtin_amdgcn_s_sleep(1); \
;     if ((++_sp & 255u) == 0u) { if (xb_ld(&(bar)[XB_TMO])) break; if (_sp > XB_SPIN_CAP) { atomicAdd(&(bar)[XB_TMO], 1u); break; } } } } while (0)
; __device__ __forceinline__ void xcd_barrier(const XcdBarrier& b, bool tid0) {
;     ...
;             XB_SPIN(xb_ld(&bar[XB_XGEN(b.x)]) == gen, bar);
;             __builtin_amdgcn_fence(__ATOMIC_ACQUIRE, "agent");
;             asm volatile("s_waitcnt vmcnt(0)" ::: "memory");
.LBB0_838:
	s_or_b64 exec, exec, s[12:13]
	s_waitcnt vmcnt(0)
	s_waitcnt vmcnt(0)

; __device__ __forceinline__ unsigned xb_add(unsigned* p, unsigned v) { return __hip_atomic_fetch_add(p, v, __ATOMIC_RELAXED, __HIP_MEMORY_SCOPE_AGENT); }
; __device__ __forceinline__ void xcd_barrier(const XcdBarrier& b, bool tid0) {
;     ...
;             __builtin_amdgcn_fence(__ATOMIC_ACQUIRE, "agent");
;             xb_add(&bar[XB_XGEN(b.x)], 1u);
.Lfastbar_3:
	s_mov_b64 s[0:1], exec
	v_mbcnt_lo_u32_b32 v0, s0, 0
	v_mbcnt_hi_u32_b32 v0, s1, v0
	v_cmp_eq_u32_e32 vcc, 0, v0
	s_waitcnt vmcnt(0)
	s_and_saveexec_b64 s[6:7], vcc
	s_cbranch_execz .LBB0_858
	s_bcnt1_i32_b64 s0, s[0:1]
	v_mov_b32_e32 v0, s0
	global_atomic_add v254, v0, s[8:9] offset:1024
.LBB0_858:
	s_or_b64 exec, exec, s[6:7]
	buffer_inv sc1
	s_waitcnt vmcnt(0)

; __device__ __forceinline__ unsigned xb_ld(unsigned* p)              { return __hip_atomic_load(p, __ATOMIC_RELAXED, __HIP_MEMORY_SCOPE_AGENT); }
; __device__ __forceinline__ unsigned xb_add(unsigned* p, unsigned v) { return __hip_atomic_fetch_add(p, v, __ATOMIC_RELAXED, __HIP_MEMORY_SCOPE_AGENT); }
; #define XB_SPIN(cond, bar) do { unsigned _sp = 0; while (cond) { __builtin_amdgcn_s_sleep(1); \
;     if ((++_sp & 255u) == 0u) { if (xb_ld(&(bar)[XB_TMO])) break; if (_sp > XB_SPIN_CAP) { atomicAdd(&(bar)[XB_TMO], 1u); break; } } } } while (0)
; __device__ __forceinline__ void xcd_barrier(const XcdBarrier& b, bool tid0) {
;     ...
;         const unsigned old = xb_add(&bar[XB_XSUB(b.x)], 1u);
;         const unsigned gen = old / nloc;
;         if (old + 1u == (gen + 1u) * nloc) {
;             __builtin_amdgcn_fence(__ATOMIC_RELEASE, "agent");
;             asm volatile("s_waitcnt vmcnt(0)" ::: "memory");
;             const unsigned og = xb_add(&bar[XB_TOP], 1u);
;             const unsigned tg = og / nx;
;             if (og + 1u == (tg + 1u) * nx) xb_add(&bar[XB_TOPGEN], 1u);
;             else XB_SPIN(xb_ld(&bar[XB_TOPGEN]) == tg, bar);
;             __builtin_amdgcn_fence(__ATOMIC_ACQUIRE, "agent");
;             xb_add(&bar[XB_XGEN(b.x)], 1u);
;             asm volatile("s_waitcnt vmcnt(0)" ::: "memory");
;         } else {
;             XB_SPIN(xb_ld(&bar[XB_XGEN(b.x)]) == gen, bar);
;             __builtin_amdgcn_fence(__ATOMIC_ACQUIRE, "agent");
;             asm volatile("s_waitcnt vmcnt(0)" ::: "memory");
.LBB0_896:
	s_or_b64 exec, exec, s[8:9]
	v_cvt_f32_u32_e32 v4, v2
	s_waitcnt vmcnt(0)
	v_readfirstlane_b32 s0, v3
	v_sub_u32_e32 v3, 0, v2
	v_rcp_iflag_f32_e32 v4, v4
	v_add_u32_e32 v5, s0, v1
	v_mul_f32_e32 v4, 0x4f7ffffe, v4
	v_cvt_u32_f32_e32 v4, v4
	v_mul_lo_u32 v1, v3, v4
	v_mul_hi_u32 v1, v4, v1
	v_add_u32_e32 v1, v4, v1
	v_mul_hi_u32 v1, v5, v1
	v_mul_lo_u32 v3, v1, v2
	v_sub_u32_e32 v3, v5, v3
	v_add_u32_e32 v4, 1, v1
	v_cmp_ge_u32_e32 vcc, v3, v2
	s_nop 1
	v_cndmask_b32_e32 v1, v1, v4, vcc
	v_sub_u32_e32 v4, v3, v2
	v_cndmask_b32_e32 v3, v3, v4, vcc
	v_add_u32_e32 v4, 1, v1
	v_cmp_ge_u32_e32 vcc, v3, v2
	v_add_u32_e32 v3, 1, v5
	s_nop 0
	v_cndmask_b32_e32 v1, v1, v4, vcc
	v_mul_lo_u32 v4, v2, v1
	v_add_u32_e32 v2, v4, v2
	v_cmp_ne_u32_e32 vcc, v3, v2
	s_and_saveexec_b64 s[0:1], vcc
	s_xor_b64 s[8:9], exec, s[0:1]
	s_cbranch_execz .LBB0_910
	s_waitcnt lgkmcnt(0)
	buffer_inv sc1
	global_load_dword v0, v254, s[6:7] offset:1024 sc1
	s_add_u32 s12, s6, 0x2400
	s_addc_u32 s13, s7, 0
	s_waitcnt vmcnt(0)
	v_cmp_eq_u32_e32 vcc, v0, v1
	s_and_saveexec_b64 s[10:11], vcc
	s_cbranch_execz .LBB0_909
	s_mov_b32 s22, 1
	s_mov_b64 s[14:15], 0
	s_branch .LBB0_900

; __device__ __forceinline__ unsigned xb_ld(unsigned* p)              { return __hip_atomic_load(p, __ATOMIC_RELAXED, __HIP_MEMORY_SCOPE_AGENT); }
; __device__ __forceinline__ unsigned xb_add(unsigned* p, unsigned v) { return __hip_atomic_fetch_add(p, v, __ATOMIC_RELAXED, __HIP_MEMORY_SCOPE_AGENT); }
; #define XB_SPIN(cond, bar) do { unsigned _sp = 0; while (cond) { __builtin_amdgcn_s_sleep(1); \
;     if ((++_sp & 255u) == 0u) { if (xb_ld(&(bar)[XB_TMO])) break; if (_sp > XB_SPIN_CAP) { atomicAdd(&(bar)[XB_TMO], 1u); break; } } } } while (0)
; __device__ __forceinline__ void xcd_barrier(const XcdBarrier& b, bool tid0) {
;     ...
;         const unsigned old = xb_add(&bar[XB_XSUB(b.x)], 1u);
;         const unsigned gen = old / nloc;
;         if (old + 1u == (gen + 1u) * nloc) {
;             __builtin_amdgcn_fence(__ATOMIC_RELEASE, "agent");
;             asm volatile("s_waitcnt vmcnt(0)" ::: "memory");
;             const unsigned og = xb_add(&bar[XB_TOP], 1u);
;             const unsigned tg = og / nx;
;             if (og + 1u == (tg + 1u) * nx) xb_add(&bar[XB_TOPGEN], 1u);
;             else XB_SPIN(xb_ld(&bar[XB_TOPGEN]) == tg, bar);
;             __builtin_amdgcn_fence(__ATOMIC_ACQUIRE, "agent");
;             xb_add(&bar[XB_XGEN(b.x)], 1u);
;             asm volatile("s_waitcnt vmcnt(0)" ::: "memory");
;         } else {
;             XB_SPIN(xb_ld(&bar[XB_XGEN(b.x)]) == gen, bar);
;             __builtin_amdgcn_fence(__ATOMIC_ACQUIRE, "agent");
;             asm volatile("s_waitcnt vmcnt(0)" ::: "memory");
.LBB0_949:
	s_or_b64 exec, exec, s[8:9]
	v_cvt_f32_u32_e32 v4, v2
	s_waitcnt vmcnt(0)
	v_readfirstlane_b32 s0, v3
	v_sub_u32_e32 v3, 0, v2
	v_rcp_iflag_f32_e32 v4, v4
	v_add_u32_e32 v5, s0, v1
	v_mul_f32_e32 v4, 0x4f7ffffe, v4
	v_cvt_u32_f32_e32 v4, v4
	v_mul_lo_u32 v1, v3, v4
	v_mul_hi_u32 v1, v4, v1
	v_add_u32_e32 v1, v4, v1
	v_mul_hi_u32 v1, v5, v1
	v_mul_lo_u32 v3, v1, v2
	v_sub_u32_e32 v3, v5, v3
	v_add_u32_e32 v4, 1, v1
	v_cmp_ge_u32_e32 vcc, v3, v2
	s_nop 1
	v_cndmask_b32_e32 v1, v1, v4, vcc
	v_sub_u32_e32 v4, v3, v2
	v_cndmask_b32_e32 v3, v3, v4, vcc
	v_add_u32_e32 v4, 1, v1
	v_cmp_ge_u32_e32 vcc, v3, v2
	v_add_u32_e32 v3, 1, v5
	s_nop 0
	v_cndmask_b32_e32 v1, v1, v4, vcc
	v_mul_lo_u32 v4, v2, v1
	v_add_u32_e32 v2, v4, v2
	v_cmp_ne_u32_e32 vcc, v3, v2
	s_and_saveexec_b64 s[0:1], vcc
	s_xor_b64 s[8:9], exec, s[0:1]
	s_cbranch_execz .LBB0_963
	s_waitcnt lgkmcnt(0)
	buffer_inv sc1
	global_load_dword v0, v254, s[6:7] offset:1024 sc1
	s_add_u32 s14, s6, 0x2400
	s_addc_u32 s15, s7, 0
	s_waitcnt vmcnt(0)
	v_cmp_eq_u32_e32 vcc, v0, v1
	s_and_saveexec_b64 s[10:11], vcc
	s_cbranch_execz .LBB0_962
	s_add_u32 s12, s4, 0x26120200
	s_addc_u32 s13, s5, 0
	s_mov_b32 s24, 1
	s_mov_b64 s[16:17], 0
	s_branch .LBB0_953

; __device__ __forceinline__ unsigned xb_ld(unsigned* p)              { return __hip_atomic_load(p, __ATOMIC_RELAXED, __HIP_MEMORY_SCOPE_AGENT); }
; __device__ __forceinline__ unsigned xb_add(unsigned* p, unsigned v) { return __hip_atomic_fetch_add(p, v, __ATOMIC_RELAXED, __HIP_MEMORY_SCOPE_AGENT); }
; #define XB_SPIN(cond, bar) do { unsigned _sp = 0; while (cond) { __builtin_amdgcn_s_sleep(1); \
;     if ((++_sp & 255u) == 0u) { if (xb_ld(&(bar)[XB_TMO])) break; if (_sp > XB_SPIN_CAP) { atomicAdd(&(bar)[XB_TMO], 1u); break; } } } } while (0)
; __device__ __forceinline__ void xcd_barrier(const XcdBarrier& b, bool tid0) {
;     ...
;         const unsigned old = xb_add(&bar[XB_XSUB(b.x)], 1u);
;         const unsigned gen = old / nloc;
;         if (old + 1u == (gen + 1u) * nloc) {
;             __builtin_amdgcn_fence(__ATOMIC_RELEASE, "agent");
;             asm volatile("s_waitcnt vmcnt(0)" ::: "memory");
;             const unsigned og = xb_add(&bar[XB_TOP], 1u);
;             const unsigned tg = og / nx;
;             if (og + 1u == (tg + 1u) * nx) xb_add(&bar[XB_TOPGEN], 1u);
;             else XB_SPIN(xb_ld(&bar[XB_TOPGEN]) == tg, bar);
;             __builtin_amdgcn_fence(__ATOMIC_ACQUIRE, "agent");
;             xb_add(&bar[XB_XGEN(b.x)], 1u);
;             asm volatile("s_waitcnt vmcnt(0)" ::: "memory");
;         } else {
;             XB_SPIN(xb_ld(&bar[XB_XGEN(b.x)]) == gen, bar);
;             __builtin_amdgcn_fence(__ATOMIC_ACQUIRE, "agent");
;             asm volatile("s_waitcnt vmcnt(0)" ::: "memory");
.LBB0_1016:
	s_or_b64 exec, exec, s[0:1]
	v_cvt_f32_u32_e32 v4, v2
	s_waitcnt vmcnt(0)
	v_readfirstlane_b32 s0, v3
	v_sub_u32_e32 v3, 0, v2
	v_rcp_iflag_f32_e32 v4, v4
	v_add_u32_e32 v5, s0, v1
	v_mul_f32_e32 v4, 0x4f7ffffe, v4
	v_cvt_u32_f32_e32 v4, v4
	v_mul_lo_u32 v1, v3, v4
	v_mul_hi_u32 v1, v4, v1
	v_add_u32_e32 v1, v4, v1
	v_mul_hi_u32 v1, v5, v1
	v_mul_lo_u32 v3, v1, v2
	v_sub_u32_e32 v3, v5, v3
	v_add_u32_e32 v4, 1, v1
	v_cmp_ge_u32_e32 vcc, v3, v2
	s_nop 1
	v_cndmask_b32_e32 v1, v1, v4, vcc
	v_sub_u32_e32 v4, v3, v2
	v_cndmask_b32_e32 v3, v3, v4, vcc
	v_add_u32_e32 v4, 1, v1
	v_cmp_ge_u32_e32 vcc, v3, v2
	v_add_u32_e32 v3, 1, v5
	s_nop 0
	v_cndmask_b32_e32 v1, v1, v4, vcc
	v_mul_lo_u32 v4, v2, v1
	v_add_u32_e32 v2, v4, v2
	v_cmp_ne_u32_e32 vcc, v3, v2
	s_and_saveexec_b64 s[0:1], vcc
	s_xor_b64 s[64:65], exec, s[0:1]
	s_cbranch_execz .LBB0_1030
	s_waitcnt lgkmcnt(0)
	buffer_inv sc1
	global_load_dword v0, v177, s[52:53] sc1
	s_waitcnt vmcnt(0)
	v_cmp_eq_u32_e32 vcc, v0, v1
	s_and_saveexec_b64 s[42:43], vcc
	s_cbranch_execz .LBB0_1029
	s_mov_b32 s24, 1
	s_mov_b64 s[4:5], 0
	s_branch .LBB0_1020

; __device__ __forceinline__ unsigned xb_ld(unsigned* p)              { return __hip_atomic_load(p, __ATOMIC_RELAXED, __HIP_MEMORY_SCOPE_AGENT); }
; #define XB_SPIN(cond, bar) do { unsigned _sp = 0; while (cond) { __builtin_amdgcn_s_sleep(1); \
;     if ((++_sp & 255u) == 0u) { if (xb_ld(&(bar)[XB_TMO])) break; if (_sp > XB_SPIN_CAP) { atomicAdd(&(bar)[XB_TMO], 1u); break; } } } } while (0)
; __device__ __forceinline__ void xcd_barrier(const XcdBarrier& b, bool tid0) {
;     ...
;             XB_SPIN(xb_ld(&bar[XB_XGEN(b.x)]) == gen, bar);
;             __builtin_amdgcn_fence(__ATOMIC_ACQUIRE, "agent");
;             asm volatile("s_waitcnt vmcnt(0)" ::: "memory");
.LBB0_1029:
	s_or_b64 exec, exec, s[42:43]
	s_waitcnt vmcnt(0)
	s_waitcnt vmcnt(0)

; __device__ __forceinline__ unsigned xb_add(unsigned* p, unsigned v) { return __hip_atomic_fetch_add(p, v, __ATOMIC_RELAXED, __HIP_MEMORY_SCOPE_AGENT); }
; __device__ __forceinline__ void xcd_barrier(const XcdBarrier& b, bool tid0) {
;     ...
;             __builtin_amdgcn_fence(__ATOMIC_ACQUIRE, "agent");
;             xb_add(&bar[XB_XGEN(b.x)], 1u);
.Lfastbar_5:
	s_mov_b64 s[0:1], exec
	v_mbcnt_lo_u32_b32 v0, s0, 0
	v_mbcnt_hi_u32_b32 v0, s1, v0
	v_cmp_eq_u32_e32 vcc, 0, v0
	s_waitcnt vmcnt(0)
	s_and_saveexec_b64 s[4:5], vcc
	s_cbranch_execz .LBB0_1049
	s_bcnt1_i32_b64 s0, s[0:1]
	v_mov_b32_e32 v0, s0
	global_atomic_add v177, v0, s[52:53]
